# P7: big-tile K-tile 0 staged by LDS-DMA right after the grid barrier (before split-K tile), rstd1 partial loads hoisted and reduced after split-K tile, split-K LDS buffer relocated
# speedup vs baseline: 1.0171x; 1.0001x over previous
.LBB0_915:
	s_or_b64 exec, exec, s[0:1]
	s_waitcnt lgkmcnt(0)
	v_cndmask_b32_e64 v0, 0, 1, s[10:11]
	v_cmp_ne_u32_e64 s[4:5], 1, v0
	s_andn2_b64 vcc, exec, s[10:11]
	s_barrier
	s_and_b32 s98, s2, 7
	s_lshl_b32 s98, s98, 3
	s_bfe_u32 s99, s2, 0x30003
	s_or_b32 s98, s98, s99
	s_lshr_b32 s99, s2, 6
	v_lshlrev_b32_e32 v150, 4, v136
	v_and_b32_e32 v151, 0x3ff, v150
	v_lshrrev_b32_e32 v152, 4, v151
	v_and_b32_e32 v152, 32, v152
	v_xor_b32_e32 v151, v151, v152
	v_lshrrev_b32_e32 v152, 10, v150
	v_lshrrev_b32_e32 v153, 1, v152
	v_lshlrev_b32_e32 v153, 15, v153
	v_and_b32_e32 v152, 1, v152
	v_lshl_or_b32 v153, v152, 6, v153
	v_lshrrev_b32_e32 v152, 6, v151
	v_lshl_or_b32 v153, v152, 11, v153
	v_and_b32_e32 v151, 63, v151
	v_or_b32_e32 v150, v153, v151
	v_add_u32_e32 v151, 0x20000, v150
	s_lshl_b32 s72, s98, 19
	s_add_u32 s74, s60, s72
	s_addc_u32 s75, s61, 0
	v_readlane_b32 s76, v254, 1
	v_readlane_b32 s77, v254, 2
	s_lshl_b32 s72, s99, 19
	s_nop 1
	s_add_u32 s76, s76, s72
	s_addc_u32 s77, s77, 0
	s_add_u32 s78, s76, 0x40000
	s_addc_u32 s79, s77, 0
	s_add_u32 s80, s74, 0x40000
	s_addc_u32 s81, s75, 0
	v_readfirstlane_b32 s82, v136
	s_nop 0
	s_lshr_b32 s82, s82, 6
	s_lshl_b32 s82, s82, 10
	s_add_i32 m0, s82, 0x10000
	s_nop 0
	global_load_lds_dwordx4 v150, s[76:77]
	s_add_i32 m0, s82, 0x12000
	s_nop 0
	global_load_lds_dwordx4 v151, s[76:77]
	s_add_i32 m0, s82, 0x0
	s_nop 0
	global_load_lds_dwordx4 v150, s[74:75]
	s_add_i32 m0, s82, 0x2000
	s_nop 0
	global_load_lds_dwordx4 v151, s[74:75]
	s_add_i32 m0, s82, 0x14000
	s_nop 0
	global_load_lds_dwordx4 v150, s[78:79]
	s_add_i32 m0, s82, 0x16000
	s_nop 0
	global_load_lds_dwordx4 v151, s[78:79]
	s_add_i32 m0, s82, 0x4000
	s_nop 0
	global_load_lds_dwordx4 v150, s[80:81]
	s_add_i32 m0, s82, 0x6000
	s_nop 0
	global_load_lds_dwordx4 v151, s[80:81]
	v_and_b32_e32 v168, 0xff, v136
	v_lshrrev_b32_e32 v169, 8, v136
	v_mul_u32_u24_e32 v169, 0x84000, v169
	v_lshl_add_u32 v168, v168, 2, v169
	s_lshl_b32 s83, s98, 10
	s_add_u32 s84, s56, s83
	s_addc_u32 s85, s57, 0
	global_load_dword v160, v168, s[84:85]
	s_add_u32 s84, s84, 0x10800
	s_addc_u32 s85, s85, 0
	global_load_dword v161, v168, s[84:85]
	s_add_u32 s84, s84, 0x10800
	s_addc_u32 s85, s85, 0
	global_load_dword v162, v168, s[84:85]
	s_add_u32 s84, s84, 0x10800
	s_addc_u32 s85, s85, 0
	global_load_dword v163, v168, s[84:85]
	s_add_u32 s84, s84, 0x10800
	s_addc_u32 s85, s85, 0
	global_load_dword v164, v168, s[84:85]
	s_add_u32 s84, s84, 0x10800
	s_addc_u32 s85, s85, 0
	global_load_dword v165, v168, s[84:85]
	s_add_u32 s84, s84, 0x10800
	s_addc_u32 s85, s85, 0
	global_load_dword v166, v168, s[84:85]
	s_add_u32 s84, s84, 0x10800
	s_addc_u32 s85, s85, 0
	global_load_dword v167, v168, s[84:85]
	s_andn2_b64 vcc, exec, s[10:11]
	s_cbranch_vccz .Lp7_sk
	s_waitcnt vmcnt(0)
	s_branch .LBB0_920
.Lp7_sk:
	v_readlane_b32 s12, v253, 51
	v_and_b32_e32 v0, 0x7800, v190
	v_mov_b32_e32 v1, 0
	v_readlane_b32 s26, v254, 1
	v_readlane_b32 s27, v254, 2
	v_mov_b32_e32 v133, v1
	v_and_b32_e32 v7, 4, v188
	v_lshl_add_u64 v[2:3], s[26:27], 0, v[0:1]
	v_lshl_add_u64 v[4:5], v[2:3], 0, v[132:133]
	v_lshl_add_u64 v[2:3], s[60:61], 0, v[0:1]
	v_lshl_add_u64 v[2:3], v[2:3], 0, v[132:133]
	v_lshlrev_b32_e32 v0, 8, v187
	v_and_or_b32 v6, v182, 16, v7
	v_readlane_b32 s14, v253, 53
	v_readlane_b32 s15, v253, 54
	v_readlane_b32 s16, v253, 55
	v_readlane_b32 s17, v253, 56
	v_readlane_b32 s18, v253, 57
	v_readlane_b32 s19, v253, 58
	v_readlane_b32 s20, v253, 59
	v_readlane_b32 s21, v253, 60
	v_readlane_b32 s22, v253, 61
	v_lshl_add_u64 v[2:3], v[2:3], 0, v[0:1]
	v_lshl_add_u64 v[4:5], v[4:5], 0, v[0:1]
	v_lshlrev_b32_e32 v0, 13, v187
	v_lshl_add_u32 v8, v189, 2, 0
	s_movk_i32 s0, 0x100
	v_and_b32_e32 v9, 60, v252
	v_lshlrev_b32_e32 v6, 8, v6
	s_mov_b32 s7, 0
	v_cmp_gt_u32_e32 vcc, s0, v136
	v_add3_u32 v6, v186, v9, v6
	v_lshl_or_b32 v7, v183, 3, v7
	s_lshl_b32 s3, s2, 1
	s_lshl_b32 s14, s38, 1
	s_lshl_b32 s15, s2, 2
	s_lshl_b32 s16, s38, 2
	s_lshl_b32 s17, s2, 5
	s_lshl_b32 s18, s38, 5
	s_mov_b32 s19, 0x8000
	s_mov_b32 s20, 0x40000
	s_mov_b32 s21, 0x48000
	v_add_u32_e32 v8, v8, v0
	v_lshrrev_b32_e32 v185, 2, v187
	v_lshl_add_u32 v8, v185, 15, v8
	v_add_u32_e32 v8, 0x8000, v8
	v_add_u32_e32 v184, 0x10000, v6
	s_mov_b32 s22, s2
	v_readlane_b32 s13, v253, 52
	v_readlane_b32 s23, v253, 62
	v_readlane_b32 s24, v253, 63
	v_readlane_b32 s25, v254, 0
	s_branch .LBB0_918

.LBB0_918:
	s_and_b32 s0, s15, 0xffffff00
	s_and_b32 s1, s3, 0x60
	s_or_b32 s12, s0, s1
	s_and_b32 s6, s17, 0x1e0
	s_ashr_i32 s13, s12, 31
	s_lshl_b64 s[0:1], s[12:13], 11
	s_or_b32 s13, s6, 0x4000
	s_lshl_b32 s6, s13, 11
	v_lshl_add_u64 v[72:73], v[2:3], 0, s[6:7]
	v_lshl_add_u64 v[70:71], v[4:5], 0, s[0:1]
	v_add_co_u32_e64 v74, s[0:1], s19, v72
	global_load_dwordx4 v[10:13], v[70:71], off
	s_nop 0
	v_addc_co_u32_e64 v75, s[0:1], 0, v73, s[0:1]
	v_add_co_u32_e64 v76, s[0:1], s19, v70
	global_load_dwordx4 v[14:17], v[72:73], off
	s_nop 0
	v_addc_co_u32_e64 v77, s[0:1], 0, v71, s[0:1]
	v_add_co_u32_e64 v78, s[0:1], s20, v70
	global_load_dwordx4 v[18:21], v[72:73], off offset:64
	global_load_dwordx4 v[22:25], v[74:75], off
	v_addc_co_u32_e64 v79, s[0:1], 0, v71, s[0:1]
	v_add_co_u32_e64 v80, s[0:1], s21, v70
	global_load_dwordx4 v[26:29], v[70:71], off offset:64
	s_nop 0
	v_addc_co_u32_e64 v81, s[0:1], 0, v71, s[0:1]
	global_load_dwordx4 v[34:37], v[76:77], off
	global_load_dwordx4 v[38:41], v[74:75], off offset:64
	global_load_dwordx4 v[42:45], v[76:77], off offset:64
	global_load_dwordx4 v[50:53], v[78:79], off
	global_load_dwordx4 v[54:57], v[78:79], off offset:64
	global_load_dwordx4 v[62:65], v[80:81], off
	global_load_dwordx4 v[66:69], v[80:81], off offset:64
	s_waitcnt vmcnt(10)
	v_mfma_f32_16x16x32_bf16 v[30:33], v[10:13], v[14:17], 0
	s_waitcnt vmcnt(8)
	v_mfma_f32_16x16x32_bf16 v[10:13], v[10:13], v[22:25], 0
	s_waitcnt vmcnt(6)
	v_mfma_f32_16x16x32_bf16 v[46:49], v[34:37], v[14:17], 0
	v_mfma_f32_16x16x32_bf16 v[34:37], v[34:37], v[22:25], 0
	s_waitcnt vmcnt(3)
	v_mfma_f32_16x16x32_bf16 v[58:61], v[50:53], v[14:17], 0
	s_waitcnt vmcnt(1)
	v_mfma_f32_16x16x32_bf16 v[14:17], v[62:65], v[14:17], 0
	v_mfma_f32_16x16x32_bf16 v[30:33], v[26:29], v[18:21], v[30:33]
	v_mfma_f32_16x16x32_bf16 v[10:13], v[26:29], v[38:41], v[10:13]
	v_mfma_f32_16x16x32_bf16 v[26:29], v[42:45], v[18:21], v[46:49]
	v_mfma_f32_16x16x32_bf16 v[34:37], v[42:45], v[38:41], v[34:37]
	v_mfma_f32_16x16x32_bf16 v[42:45], v[54:57], v[18:21], v[58:61]
	s_waitcnt vmcnt(0)
	v_mfma_f32_16x16x32_bf16 v[14:17], v[66:69], v[18:21], v[14:17]
	global_load_dwordx4 v[18:21], v[70:71], off offset:128
	v_mfma_f32_16x16x32_bf16 v[50:53], v[50:53], v[22:25], 0
	v_mfma_f32_16x16x32_bf16 v[22:25], v[62:65], v[22:25], 0
	v_mfma_f32_16x16x32_bf16 v[46:49], v[54:57], v[38:41], v[50:53]
	v_mfma_f32_16x16x32_bf16 v[22:25], v[66:69], v[38:41], v[22:25]
	global_load_dwordx4 v[38:41], v[72:73], off offset:128
	s_nop 3
	global_load_dwordx4 v[50:53], v[72:73], off offset:192
	global_load_dwordx4 v[54:57], v[70:71], off offset:192
	global_load_dwordx4 v[58:61], v[74:75], off offset:128
	global_load_dwordx4 v[62:65], v[74:75], off offset:192
	s_waitcnt vmcnt(4)
	v_mfma_f32_16x16x32_bf16 v[30:33], v[18:21], v[38:41], v[30:33]
	s_waitcnt vmcnt(1)
	v_mfma_f32_16x16x32_bf16 v[10:13], v[18:21], v[58:61], v[10:13]
	global_load_dwordx4 v[18:21], v[76:77], off offset:128
	global_load_dwordx4 v[66:69], v[76:77], off offset:192
	v_mfma_f32_16x16x32_bf16 v[30:33], v[54:57], v[50:53], v[30:33]
	s_waitcnt vmcnt(2)
	v_mfma_f32_16x16x32_bf16 v[10:13], v[54:57], v[62:65], v[10:13]
	s_waitcnt vmcnt(1)
	v_mfma_f32_16x16x32_bf16 v[26:29], v[18:21], v[38:41], v[26:29]
	v_mfma_f32_16x16x32_bf16 v[18:21], v[18:21], v[58:61], v[34:37]
	s_nop 2
	global_load_dwordx4 v[34:37], v[78:79], off offset:128
	global_load_dwordx4 v[70:73], v[78:79], off offset:192
	global_load_dwordx4 v[74:77], v[80:81], off offset:128
	s_waitcnt vmcnt(3)
	v_mfma_f32_16x16x32_bf16 v[26:29], v[66:69], v[50:53], v[26:29]
	s_waitcnt vmcnt(2)
	v_mfma_f32_16x16x32_bf16 v[42:45], v[34:37], v[38:41], v[42:45]
	v_mfma_f32_16x16x32_bf16 v[34:37], v[34:37], v[58:61], v[46:49]
	s_nop 2
	global_load_dwordx4 v[46:49], v[80:81], off offset:192
	s_waitcnt vmcnt(1)
	v_mfma_f32_16x16x32_bf16 v[14:17], v[74:77], v[38:41], v[14:17]
	s_barrier
	ds_write2st64_b32 v8, v30, v31 offset1:1
	ds_write2st64_b32 v8, v32, v33 offset0:2 offset1:3
	v_mfma_f32_16x16x32_bf16 v[30:33], v[70:73], v[50:53], v[42:45]
	ds_write2st64_b32 v8, v26, v27 offset0:4 offset1:5
	ds_write2st64_b32 v8, v28, v29 offset0:6 offset1:7
	s_nop 5
	ds_write2st64_b32 v8, v30, v31 offset0:8 offset1:9
	v_mfma_f32_16x16x32_bf16 v[22:25], v[74:77], v[58:61], v[22:25]
	s_waitcnt vmcnt(0)
	v_mfma_f32_16x16x32_bf16 v[14:17], v[46:49], v[50:53], v[14:17]
	ds_write2st64_b32 v8, v32, v33 offset0:10 offset1:11
	s_nop 6
	ds_write2st64_b32 v8, v14, v15 offset0:12 offset1:13
	ds_write2st64_b32 v8, v16, v17 offset0:14 offset1:15
	v_mfma_f32_16x16x32_bf16 v[14:17], v[66:69], v[62:65], v[18:21]
	ds_write2st64_b32 v8, v10, v11 offset0:16 offset1:17
	ds_write2st64_b32 v8, v12, v13 offset0:18 offset1:19
	s_nop 5
	ds_write2st64_b32 v8, v14, v15 offset0:20 offset1:21
	v_mfma_f32_16x16x32_bf16 v[10:13], v[70:73], v[62:65], v[34:37]
	ds_write2st64_b32 v8, v16, v17 offset0:22 offset1:23
	s_nop 6
	ds_write2st64_b32 v8, v10, v11 offset0:24 offset1:25
	ds_write2st64_b32 v8, v12, v13 offset0:26 offset1:27
	v_mfma_f32_16x16x32_bf16 v[10:13], v[46:49], v[62:65], v[22:25]
	s_nop 7
	ds_write2st64_b32 v8, v10, v11 offset0:28 offset1:29
	ds_write2st64_b32 v8, v12, v13 offset0:30 offset1:31
	s_waitcnt lgkmcnt(0)
	s_barrier
	s_and_saveexec_b64 s[0:1], vcc
	s_cbranch_execz .LBB0_917
	v_or_b32_e32 v0, s13, v182
	v_lshlrev_b32_e32 v9, 2, v0
	global_load_dword v10, v9, s[46:47]
	ds_read2st64_b32 v[12:13], v6 offset0:128 offset1:129
	ds_read2st64_b32 v[14:15], v6 offset0:136 offset1:137
	ds_read2st64_b32 v[16:17], v6 offset0:138 offset1:139
	ds_read2st64_b32 v[18:19], v6 offset0:130 offset1:131
	ds_read2st64_b32 v[20:21], v6 offset0:160 offset1:161
	ds_read2st64_b32 v[22:23], v6 offset0:168 offset1:169
	ds_read2st64_b32 v[24:25], v6 offset0:170 offset1:171
	ds_read2st64_b32 v[26:27], v6 offset0:162 offset1:163
	ds_read2st64_b32 v[28:29], v6 offset0:192 offset1:193
	ds_read2st64_b32 v[30:31], v6 offset0:200 offset1:201
	ds_read2st64_b32 v[32:33], v6 offset0:202 offset1:203
	ds_read2st64_b32 v[34:35], v6 offset0:194 offset1:195
	ds_read2st64_b32 v[36:37], v6 offset0:224 offset1:225
	ds_read2st64_b32 v[38:39], v6 offset0:232 offset1:233
	ds_read2st64_b32 v[40:41], v6 offset0:234 offset1:235
	ds_read2st64_b32 v[42:43], v6 offset0:226 offset1:227
	ds_read2st64_b32 v[44:45], v184 offset0:128 offset1:129
	ds_read2st64_b32 v[46:47], v184 offset0:136 offset1:137
	ds_read2st64_b32 v[48:49], v184 offset0:138 offset1:139
	ds_read2st64_b32 v[50:51], v184 offset0:130 offset1:131
	ds_read2st64_b32 v[52:53], v184 offset0:160 offset1:161
	ds_read2st64_b32 v[54:55], v184 offset0:168 offset1:169
	ds_read2st64_b32 v[56:57], v184 offset0:170 offset1:171
	ds_read2st64_b32 v[58:59], v184 offset0:162 offset1:163
	ds_read2st64_b32 v[60:61], v184 offset0:192 offset1:193
	ds_read2st64_b32 v[62:63], v184 offset0:200 offset1:201
	ds_read2st64_b32 v[64:65], v184 offset0:202 offset1:203
	ds_read2st64_b32 v[66:67], v184 offset0:194 offset1:195
	ds_read2st64_b32 v[68:69], v184 offset0:224 offset1:225
	ds_read2st64_b32 v[70:71], v184 offset0:232 offset1:233
	ds_read2st64_b32 v[72:73], v184 offset0:234 offset1:235
	ds_read2st64_b32 v[74:75], v184 offset0:226 offset1:227
	s_waitcnt lgkmcnt(14)
	v_pk_add_f32 v[12:13], v[12:13], 0 op_sel_hi:[1,0]
	v_pk_add_f32 v[18:19], v[18:19], 0 op_sel_hi:[1,0]
	v_pk_add_f32 v[16:17], v[16:17], 0 op_sel_hi:[1,0]
	v_pk_add_f32 v[14:15], v[14:15], 0 op_sel_hi:[1,0]
	v_pk_add_f32 v[12:13], v[12:13], v[20:21]
	v_pk_add_f32 v[18:19], v[18:19], v[26:27]
	v_pk_add_f32 v[14:15], v[14:15], v[22:23]
	v_pk_add_f32 v[16:17], v[16:17], v[24:25]
	v_pk_add_f32 v[12:13], v[12:13], v[28:29]
	v_pk_add_f32 v[18:19], v[18:19], v[34:35]
	v_pk_add_f32 v[16:17], v[16:17], v[32:33]
	v_pk_add_f32 v[14:15], v[14:15], v[30:31]
	v_pk_add_f32 v[12:13], v[12:13], v[36:37]
	v_pk_add_f32 v[18:19], v[18:19], v[42:43]
	v_pk_add_f32 v[14:15], v[14:15], v[38:39]
	v_pk_add_f32 v[16:17], v[16:17], v[40:41]
	v_pk_add_f32 v[12:13], v[12:13], v[44:45]
	s_waitcnt lgkmcnt(12)
	v_pk_add_f32 v[18:19], v[18:19], v[50:51]
	v_pk_add_f32 v[16:17], v[16:17], v[48:49]
	v_pk_add_f32 v[14:15], v[14:15], v[46:47]
	s_waitcnt lgkmcnt(11)
	v_pk_add_f32 v[12:13], v[12:13], v[52:53]
	s_waitcnt lgkmcnt(8)
	v_pk_add_f32 v[18:19], v[18:19], v[58:59]
	v_pk_add_f32 v[14:15], v[14:15], v[54:55]
	v_pk_add_f32 v[16:17], v[16:17], v[56:57]
	s_waitcnt lgkmcnt(7)
	v_pk_add_f32 v[12:13], v[12:13], v[60:61]
	v_or_b32_e32 v76, s12, v7
	v_lshlrev_b32_e32 v0, 11, v0
	s_waitcnt lgkmcnt(4)
	v_pk_add_f32 v[18:19], v[18:19], v[66:67]
	v_pk_add_f32 v[16:17], v[16:17], v[64:65]
	v_pk_add_f32 v[14:15], v[14:15], v[62:63]
	s_waitcnt lgkmcnt(3)
	v_pk_add_f32 v[12:13], v[12:13], v[68:69]
	v_ashrrev_i32_e32 v77, 31, v76
	v_lshl_add_u64 v[78:79], s[62:63], 0, v[0:1]
	s_waitcnt lgkmcnt(0)
	v_pk_add_f32 v[18:19], v[18:19], v[74:75]
	v_pk_add_f32 v[14:15], v[14:15], v[70:71]
	v_pk_add_f32 v[16:17], v[16:17], v[72:73]
	v_lshl_add_u64 v[76:77], v[76:77], 1, v[78:79]
	s_waitcnt vmcnt(0)
	v_pk_mul_f32 v[12:13], v[12:13], v[10:11] op_sel_hi:[1,0]
	v_pk_mul_f32 v[18:19], v[18:19], v[10:11] op_sel_hi:[1,0]
	v_pk_mul_f32 v[16:17], v[16:17], v[10:11] op_sel_hi:[1,0]
	v_pk_mul_f32 v[10:11], v[14:15], v[10:11] op_sel_hi:[1,0]
	v_cvt_pk_bf16_f32 v12, v12, v13
	v_cvt_pk_bf16_f32 v13, v18, v19
	s_nop 0
	v_cvt_pk_bf16_f32 v10, v10, v11
	v_cvt_pk_bf16_f32 v11, v16, v17
	global_store_dwordx2 v[76:77], v[12:13], off
	global_store_dwordx2 v[76:77], v[10:11], off offset:256
	s_branch .LBB0_917
.LBB0_920:
	v_add_f32_e32 v160, v160, v161
	v_add_f32_e32 v160, v160, v162
	v_add_f32_e32 v160, v160, v163
	v_add_f32_e32 v160, v160, v164
	v_add_f32_e32 v160, v160, v165
	v_add_f32_e32 v160, v160, v166
	v_add_f32_e32 v160, v160, v167
	v_lshlrev_b32_e32 v169, 2, v136
	v_add_u32_e32 v168, 0x22000, v169
	ds_write_b32 v168, v160
	s_waitcnt lgkmcnt(0)
	s_barrier
	v_cmp_gt_u32_e32 vcc, 0x100, v136
	s_and_saveexec_b64 s[72:73], vcc
	ds_read_b32 v160, v168
	ds_read_b32 v161, v168 offset:1024
	s_mov_b32 s76, 0x3a800000
	v_mov_b32_e32 v162, 0x358637bd
	s_lshl_b32 s74, s98, 10
	s_add_u32 s74, s46, s74
	s_addc_u32 s75, s47, 0
	s_waitcnt lgkmcnt(0)
	v_add_f32_e32 v160, v160, v161
	v_fma_f32 v160, v160, s76, v162
	v_rsq_f32_e32 v160, v160
	s_nop 1
	global_store_dword v169, v160, s[74:75]
	s_or_b64 exec, exec, s[72:73]
	s_mov_b32 s3, 0
	v_mov_b32_e32 v129, 0
	s_mov_b64 s[0:1], 0x80
	s_mov_b64 s[6:7], 0x40080
	s_mov_b64 s[12:13], 0x100
	s_mov_b64 s[14:15], 0x40100
	s_mov_b64 s[16:17], 0x180
	s_mov_b64 s[18:19], 0x40180
	v_mov_b32_e32 v133, 1
	s_mov_b32 s30, s96
	s_branch .LBB0_923

.LBB0_923:
	s_lshl_b32 s20, s3, 3
	s_or_b32 s20, s20, s94
	s_mul_i32 s20, s20, s93
	s_add_i32 s20, s20, s95
	s_cmpk_gt_i32 s20, 0xff
	s_cbranch_scc1 .LBB0_922
	v_mov_b32_e32 v14, v136
	s_barrier
	s_ashr_i32 s21, s20, 31
	v_ashrrev_i32_e32 v1, 31, v14
	v_lshrrev_b32_e32 v1, 26, v1
	v_add_u32_e32 v1, v14, v1
	v_ashrrev_i32_e32 v8, 6, v1
	v_bfe_i32 v1, v14, 27, 1
	v_lshlrev_b32_e32 v0, 4, v14
	v_lshrrev_b32_e32 v1, 22, v1
	v_add_u32_e32 v1, v0, v1
	v_and_b32_e32 v1, 0xfffffc00, v1
	v_sub_u32_e32 v1, v0, v1
	v_lshrrev_b32_e32 v2, 4, v1
	v_bitop3_b32 v1, v2, v1, 32 bitop3:0x6c
	v_ashrrev_i32_e32 v3, 31, v1
	v_lshrrev_b32_e32 v3, 26, v3
	v_add_u32_e32 v3, v1, v3
	v_ashrrev_i32_e32 v9, 6, v3
	v_and_b32_e32 v3, 0xc0, v3
	v_sub_u32_e32 v1, v1, v3
	s_lshr_b32 s21, s21, 27
	v_lshlrev_b32_e32 v2, 3, v8
	v_lshlrev_b32_e32 v4, 5, v8
	v_ashrrev_i16_sdwa v1, v133, sext(v1) dst_sel:DWORD dst_unused:UNUSED_PAD src0_sel:DWORD src1_sel:BYTE_0
	s_add_i32 s21, s20, s21
	v_and_b32_e32 v2, 0x1ffff0, v2
	v_and_b32_e32 v4, 32, v4
	v_bfe_i32 v11, v1, 0, 16
	s_ashr_i32 s40, s21, 5
	s_andn2_b32 s21, s21, 31
	v_add_u32_e32 v1, v4, v11
	v_add_lshl_u32 v2, v9, v2, 11
	v_add_u32_e32 v0, 0x2000, v0
	s_sub_i32 s21, s20, s21
	v_lshl_add_u32 v128, v1, 1, v2
	v_ashrrev_i32_e32 v1, 31, v0
	s_ashr_i32 s20, s21, 31
	v_lshrrev_b32_e32 v1, 22, v1
	s_lshr_b32 s20, s20, 29
	v_add_u32_e32 v1, v0, v1
	s_lshl_b32 s22, s40, 3
	s_add_i32 s23, s21, s20
	v_ashrrev_i32_e32 v10, 10, v1
	s_add_i32 s21, s21, s22
	s_and_b32 s41, s23, -8
	v_mul_i32_i24_e32 v1, 0x400, v10
	s_sub_i32 s22, s21, s41
	v_sub_u32_e32 v0, v0, v1
	s_ashr_i32 s20, s23, 3
	s_ashr_i32 s23, s22, 31
	v_lshrrev_b32_e32 v1, 4, v0
	s_lshl_b64 s[24:25], s[22:23], 19
	v_bitop3_b32 v0, v1, v0, 32 bitop3:0x6c
	s_add_u32 s24, s60, s24
	v_readlane_b32 s72, v253, 51
	v_ashrrev_i32_e32 v2, 31, v0
	s_addc_u32 s25, s61, s25
	s_ashr_i32 s21, s20, 31
	v_readlane_b32 s86, v254, 1
	v_readlane_b32 s87, v254, 2
	v_lshrrev_b32_e32 v2, 26, v2
	s_lshl_b64 s[26:27], s[20:21], 19
	s_mov_b64 s[50:51], s[86:87]
	v_add_u32_e32 v2, v0, v2
	s_add_u32 s28, s50, s26
	v_readfirstlane_b32 s21, v14
	v_ashrrev_i32_e32 v12, 6, v2
	v_and_b32_e32 v2, 0xc0, v2
	s_addc_u32 s29, s51, s27
	v_sub_u32_e32 v0, v0, v2
	s_ashr_i32 s37, s21, 6
	v_lshlrev_b32_e32 v1, 3, v10
	v_lshlrev_b32_e32 v3, 5, v10
	v_ashrrev_i16_sdwa v0, v133, sext(v0) dst_sel:DWORD dst_unused:UNUSED_PAD src0_sel:DWORD src1_sel:BYTE_0
	s_lshl_b32 s23, s37, 10
	v_and_b32_e32 v1, 0x1ffff0, v1
	v_and_b32_e32 v3, 32, v3
	v_bfe_i32 v13, v0, 0, 16
	s_add_i32 s31, s23, 0
	v_add_u32_e32 v0, v3, v13
	v_add_lshl_u32 v1, v12, v1, 11
	s_add_i32 m0, s31, 0x10000
	v_lshl_add_u32 v130, v0, 1, v1
	s_add_i32 m0, s31, 0x12000
	s_ashr_i32 s36, s21, 8
	s_mov_b32 m0, s31
	s_add_i32 s33, s31, 0x2000
	s_mov_b32 m0, s33
	s_add_u32 s34, s28, 0x40000
	s_addc_u32 s35, s29, 0
	s_add_i32 m0, s31, 0x14000
	v_mov_b32_e32 v131, v129
	s_add_i32 m0, s31, 0x16000
	s_add_u32 s50, s24, 0x40000
	s_addc_u32 s51, s25, 0
	s_add_i32 s34, s31, 0x4000
	s_mov_b32 m0, s34
	s_add_i32 s35, s31, 0x6000
	s_mov_b32 m0, s35
	v_lshl_add_u64 v[6:7], s[28:29], 0, v[128:129]
	v_lshl_add_u64 v[4:5], s[28:29], 0, v[130:131]
	v_lshl_add_u64 v[2:3], s[24:25], 0, v[128:129]
	s_cmp_lg_u32 s36, 1
	v_lshl_add_u64 v[0:1], s[24:25], 0, v[130:131]
	v_readlane_b32 s73, v253, 52
	v_readlane_b32 s74, v253, 53
	v_readlane_b32 s75, v253, 54
	v_readlane_b32 s76, v253, 55
	v_readlane_b32 s77, v253, 56
	v_readlane_b32 s78, v253, 57
	v_readlane_b32 s79, v253, 58
	v_readlane_b32 s80, v253, 59
	v_readlane_b32 s81, v253, 60
	v_readlane_b32 s82, v253, 61
	v_readlane_b32 s83, v253, 62
	v_readlane_b32 s84, v253, 63
	v_readlane_b32 s85, v254, 0
	s_cbranch_scc1 .LBB0_926
	s_barrier
.LBB0_926:
	v_and_b32_e32 v15, 15, v14
	v_and_b32_e32 v16, 48, v14
	v_lshlrev_b32_e32 v14, 2, v14
	v_lshlrev_b32_e32 v15, 6, v15
	v_and_b32_e32 v14, 32, v14
	s_lshl_b32 s37, s37, 12
	v_or_b32_e32 v17, v15, v16
	v_bitop3_b32 v15, v15, v14, v16 bitop3:0x36
	s_lshl_b32 s36, s36, 13
	s_and_b32 s37, s37, 0x3000
	s_add_i32 m0, s31, 0x18000
	v_lshl_add_u64 v[6:7], v[6:7], 0, s[0:1]
	v_or_b32_e32 v145, s37, v15
	v_bitop3_b32 v14, v17, s36, v14 bitop3:0xde
	s_waitcnt vmcnt(0)
	s_barrier
	global_load_lds_dwordx4 v[6:7], off
	v_lshl_add_u64 v[4:5], v[4:5], 0, s[0:1]
	s_add_i32 m0, s31, 0x1a000
	s_add_i32 s36, s31, 0x8000
	s_add_i32 s37, s31, 0xa000
	global_load_lds_dwordx4 v[4:5], off
	v_lshl_add_u64 v[2:3], v[2:3], 0, s[0:1]
	s_mov_b32 m0, s36
	s_add_u32 s28, s28, 0x40080
	global_load_lds_dwordx4 v[2:3], off
	v_lshl_add_u64 v[0:1], v[0:1], 0, s[0:1]
	s_mov_b32 m0, s37
	s_addc_u32 s29, s29, 0
	global_load_lds_dwordx4 v[0:1], off
	s_add_i32 m0, s31, 0x1c000
	v_lshl_add_u64 v[0:1], s[28:29], 0, v[128:129]
	global_load_lds_dwordx4 v[0:1], off
	v_lshl_add_u64 v[0:1], s[28:29], 0, v[130:131]
	s_add_i32 m0, s31, 0x1e000
	s_sub_i32 s28, s30, s41
	global_load_lds_dwordx4 v[0:1], off
	s_mul_i32 s40, s40, 24
	s_sub_i32 s28, s28, s40
	s_ashr_i32 s29, s28, 31
	s_lshl_b64 s[28:29], s[28:29], 19
	v_lshlrev_b32_e32 v0, 14, v8
	v_readlane_b32 s72, v253, 51
	v_and_b32_e32 v0, 0xffff8000, v0
	s_add_u32 s28, s60, s28
	v_lshlrev_b32_e32 v2, 14, v10
	v_readlane_b32 s86, v254, 1
	v_readlane_b32 s87, v254, 2
	v_lshl_add_u32 v0, v9, 11, v0
	v_and_b32_e32 v1, 1, v8
	s_addc_u32 s29, s61, s29
	v_and_b32_e32 v2, 0xffff8000, v2
	s_mov_b64 s[50:51], s[86:87]
	v_lshl_or_b32 v0, v1, 6, v0
	v_lshl_add_u32 v2, v12, 11, v2
	v_and_b32_e32 v3, 1, v10
	s_add_u32 s26, s50, s26
	s_waitcnt vmcnt(6)
	v_lshl_add_u32 v0, v11, 1, v0
	v_mov_b32_e32 v1, v129
	v_lshl_or_b32 v2, v3, 6, v2
	s_addc_u32 s27, s51, s27
	v_lshl_add_u64 v[134:135], s[28:29], 0, v[0:1]
	v_lshl_add_u32 v2, v13, 1, v2
	v_mov_b32_e32 v3, v129
	v_lshl_add_u64 v[140:141], s[26:27], 0, v[0:1]
	v_mov_b32_e32 v0, 0
	v_lshl_add_u64 v[138:139], s[28:29], 0, v[2:3]
	v_lshl_add_u64 v[142:143], s[26:27], 0, v[2:3]
	s_mov_b32 s29, -2
	s_mov_b64 s[26:27], 0
	v_add_u32_e32 v146, s42, v145
	v_add_u32_e32 v144, 0, v14
	s_add_i32 s40, s31, 0xc000
	s_add_i32 s28, s31, 0xe000
	v_add_u32_e32 v147, s43, v145
	v_mov_b32_e32 v1, v0
	v_mov_b32_e32 v2, v0
	v_mov_b32_e32 v3, v0
	v_mov_b32_e32 v4, v0
	v_mov_b32_e32 v5, v0
	v_mov_b32_e32 v6, v0
	v_mov_b32_e32 v7, v0
	v_mov_b32_e32 v8, v0
	v_mov_b32_e32 v9, v0
	v_mov_b32_e32 v10, v0
	v_mov_b32_e32 v11, v0
	v_mov_b32_e32 v12, v0
	v_mov_b32_e32 v13, v0
	v_mov_b32_e32 v14, v0
	v_mov_b32_e32 v15, v0
	v_mov_b32_e32 v16, v0
	v_mov_b32_e32 v17, v0
	v_mov_b32_e32 v18, v0
	v_mov_b32_e32 v19, v0
	v_mov_b32_e32 v20, v0
	v_mov_b32_e32 v21, v0
	v_mov_b32_e32 v22, v0
	v_mov_b32_e32 v23, v0
	v_mov_b32_e32 v24, v0
	v_mov_b32_e32 v25, v0
	v_mov_b32_e32 v26, v0
	v_mov_b32_e32 v27, v0
	v_mov_b32_e32 v28, v0
	v_mov_b32_e32 v29, v0
	v_mov_b32_e32 v30, v0
	v_mov_b32_e32 v31, v0
	v_mov_b32_e32 v32, v0
	v_mov_b32_e32 v33, v0
	v_mov_b32_e32 v34, v0
	v_mov_b32_e32 v35, v0
	v_mov_b32_e32 v36, v0
	v_mov_b32_e32 v37, v0
	v_mov_b32_e32 v38, v0
	v_mov_b32_e32 v39, v0
	v_mov_b32_e32 v40, v0
	v_mov_b32_e32 v41, v0
	v_mov_b32_e32 v42, v0
	v_mov_b32_e32 v43, v0
	v_mov_b32_e32 v44, v0
	v_mov_b32_e32 v45, v0
	v_mov_b32_e32 v46, v0
	v_mov_b32_e32 v47, v0
	v_mov_b32_e32 v48, v0
	v_mov_b32_e32 v49, v0
	v_mov_b32_e32 v50, v0
	v_mov_b32_e32 v51, v0
	v_mov_b32_e32 v52, v0
	v_mov_b32_e32 v53, v0
	v_mov_b32_e32 v54, v0
	v_mov_b32_e32 v55, v0
	v_mov_b32_e32 v56, v0
	v_mov_b32_e32 v57, v0
	v_mov_b32_e32 v58, v0
	v_mov_b32_e32 v59, v0
	v_mov_b32_e32 v60, v0
	v_mov_b32_e32 v61, v0
	v_mov_b32_e32 v62, v0
	v_mov_b32_e32 v63, v0
	v_mov_b32_e32 v64, v0
	v_mov_b32_e32 v65, v0
	v_mov_b32_e32 v66, v0
	v_mov_b32_e32 v67, v0
	v_mov_b32_e32 v68, v0
	v_mov_b32_e32 v69, v0
	v_mov_b32_e32 v70, v0
	v_mov_b32_e32 v71, v0
	v_mov_b32_e32 v72, v0
	v_mov_b32_e32 v73, v0
	v_mov_b32_e32 v74, v0
	v_mov_b32_e32 v75, v0
	v_mov_b32_e32 v76, v0
	v_mov_b32_e32 v77, v0
	v_mov_b32_e32 v78, v0
	v_mov_b32_e32 v79, v0
	v_mov_b32_e32 v80, v0
	v_mov_b32_e32 v81, v0
	v_mov_b32_e32 v82, v0
	v_mov_b32_e32 v83, v0
	v_mov_b32_e32 v84, v0
	v_mov_b32_e32 v85, v0
	v_mov_b32_e32 v86, v0
	v_mov_b32_e32 v87, v0
	v_mov_b32_e32 v88, v0
	v_mov_b32_e32 v89, v0
	v_mov_b32_e32 v90, v0
	v_mov_b32_e32 v91, v0
	v_mov_b32_e32 v92, v0
	v_mov_b32_e32 v93, v0
	v_mov_b32_e32 v94, v0
	v_mov_b32_e32 v95, v0
	v_mov_b32_e32 v96, v0
	v_mov_b32_e32 v97, v0
	v_mov_b32_e32 v98, v0
	v_mov_b32_e32 v99, v0
	v_mov_b32_e32 v100, v0
	v_mov_b32_e32 v101, v0
	v_mov_b32_e32 v102, v0
	v_mov_b32_e32 v103, v0
	v_mov_b32_e32 v104, v0
	v_mov_b32_e32 v105, v0
	v_mov_b32_e32 v106, v0
	v_mov_b32_e32 v107, v0
	v_mov_b32_e32 v108, v0
	v_mov_b32_e32 v109, v0
	v_mov_b32_e32 v110, v0
	v_mov_b32_e32 v111, v0
	v_mov_b32_e32 v112, v0
	v_mov_b32_e32 v113, v0
	v_mov_b32_e32 v114, v0
	v_mov_b32_e32 v115, v0
	v_mov_b32_e32 v116, v0
	v_mov_b32_e32 v117, v0
	v_mov_b32_e32 v118, v0
	v_mov_b32_e32 v119, v0
	v_mov_b32_e32 v120, v0
	v_mov_b32_e32 v121, v0
	v_mov_b32_e32 v122, v0
	v_mov_b32_e32 v123, v0
	v_mov_b32_e32 v124, v0
	v_mov_b32_e32 v125, v0
	v_mov_b32_e32 v126, v0
	v_mov_b32_e32 v127, v0
	s_barrier
	v_readlane_b32 s73, v253, 52
	v_readlane_b32 s74, v253, 53
	v_readlane_b32 s75, v253, 54
	v_readlane_b32 s76, v253, 55
	v_readlane_b32 s77, v253, 56
	v_readlane_b32 s78, v253, 57
	v_readlane_b32 s79, v253, 58
	v_readlane_b32 s80, v253, 59
	v_readlane_b32 s81, v253, 60
	v_readlane_b32 s82, v253, 61
	v_readlane_b32 s83, v253, 62
	v_readlane_b32 s84, v253, 63
	v_readlane_b32 s85, v254, 0
